# stack without the wave 4-7 priority toggles in the attention loop
# baseline (speedup 1.0000x reference)
.LBB0_458:
	s_add_i32 s78, s34, -4
	s_cmp_gt_i32 s78, s39
	s_cselect_b64 vcc, -1, 0
	s_cselect_b32 s82, s63, s60
	v_cndmask_b32_e64 v200, v201, -v201, vcc
	s_lshl_b32 s84, s82, 1
	s_addk_i32 s80, 0xc000
	s_cmp_lg_u32 s10, 0
	s_cselect_b32 s80, s80, 0x8000
	s_add_i32 s80, s14, s80
	v_lshl_add_u64 v[98:99], v[204:205], 0, s[84:85]
	s_add_i32 m0, s80, 0xc000
	v_lshl_add_u64 v[100:101], v[206:207], 0, s[84:85]
	global_load_lds_dwordx4 v[98:99], off
	s_add_i32 m0, s80, 0xc400
	v_cvt_f32_i32_e32 v98, s82
	global_load_lds_dwordx4 v[100:101], off
	v_add_u32_e32 v183, s79, v218
	v_add_f32_e32 v98, v155, v98
	v_fma_f32 v224, v200, v98, -v199
	v_fma_f32 v98, 0, v200, v224
	v_add_f32_e32 v99, v200, v224
	v_fma_f32 v100, v200, s64, v224
	v_fma_f32 v101, v200, s65, v224
	v_fma_f32 v102, v200, s66, v224
	v_fma_f32 v103, v200, s67, v224
	v_mul_f32_e32 v240, 0x42000000, v200
	ds_read_b128 v[228:231], v181 offset:53248
	s_waitcnt lgkmcnt(2)
	v_mfma_f32_32x32x16_bf16 v[18:33], v[126:129], v[106:109], v[18:33]
	v_add_f32_e32 v254, v70, v254
	v_add_f32_e32 v255, v252, v255
	v_exp_f32_e32 v71, v71
	v_fma_f32 v104, v200, s68, v224
	v_fma_f32 v105, v200, s69, v224
	ds_read_b128 v[126:129], v181 offset:57344
	v_mfma_f32_32x32x16_bf16 v[2:17], v[118:121], v[106:109], v[2:17]
	v_add_f32_e32 v254, v71, v254
	v_exp_f32_e32 v253, v87
	v_exp_f32_e32 v82, v72
	ds_read_b128 v[118:121], v181 offset:61440
	s_waitcnt lgkmcnt(2)
	v_mfma_f32_32x32x16_bf16 v[50:65], v[122:125], v[110:113], v[50:65]
	v_add_f32_e32 v255, v253, v255
	v_add_f32_e32 v254, v82, v254
	v_exp_f32_e32 v72, v88
	v_fma_f32 v106, v200, s70, v224
	v_fma_f32 v107, v200, s71, v224
	v_add_u32_e32 v179, v179, v226
	ds_read_b128 v[122:125], v179 offset:49152
	v_mfma_f32_32x32x16_bf16 v[34:49], v[228:231], v[110:113], v[34:49]
	v_add_f32_e32 v255, v72, v255
	v_exp_f32_e32 v83, v73
	v_exp_f32_e32 v73, v89
	ds_read_b128 v[228:231], v179 offset:53248
	s_waitcnt lgkmcnt(2)
	v_mfma_f32_32x32x16_bf16 v[18:33], v[126:129], v[110:113], v[18:33]
	v_add_f32_e32 v254, v83, v254
	v_add_f32_e32 v255, v73, v255
	v_exp_f32_e32 v74, v74
	v_fma_f32 v108, v200, s72, v224
	v_fma_f32 v109, v200, s73, v224
	ds_read_b128 v[126:129], v179 offset:57344
	v_mfma_f32_32x32x16_bf16 v[2:17], v[118:121], v[110:113], v[2:17]
	v_add_f32_e32 v254, v74, v254
	v_exp_f32_e32 v90, v90
	v_exp_f32_e32 v75, v75
	ds_read_b128 v[118:121], v179 offset:61440
	s_waitcnt lgkmcnt(2)
	v_mfma_f32_32x32x16_bf16 v[50:65], v[122:125], v[114:117], v[50:65]
	v_add_f32_e32 v255, v90, v255
	v_add_f32_e32 v254, v75, v254
	v_exp_f32_e32 v91, v91
	v_fma_f32 v110, v200, s74, v224
	v_fma_f32 v111, v200, s75, v224
	v_add_u32_e32 v112, v183, v149
	ds_read_b128 v[232:235], v112
	v_mfma_f32_32x32x16_bf16 v[34:49], v[228:231], v[114:117], v[34:49]
	v_add_f32_e32 v255, v91, v255
	v_exp_f32_e32 v76, v76
	v_exp_f32_e32 v92, v92
	ds_read_b128 v[228:231], v112 offset:4096
	s_waitcnt lgkmcnt(2)
	v_mfma_f32_32x32x16_bf16 v[18:33], v[126:129], v[114:117], v[18:33]
	v_add_f32_e32 v254, v76, v254
	v_add_f32_e32 v255, v92, v255
	v_exp_f32_e32 v77, v77
	v_fma_f32 v112, v200, s76, v224
	v_fma_f32 v113, v200, s77, v224
	v_add_u32_e32 v179, v183, v208
	ds_read_b128 v[236:239], v179
	v_mfma_f32_32x32x16_bf16 v[2:17], v[118:121], v[114:117], v[2:17]
	v_add_f32_e64 v114, v240, v98
	v_add_f32_e64 v115, v240, v99
	v_add_f32_e64 v128, v240, v112
	v_add_f32_e64 v129, v240, v113
	v_add_f32_e64 v126, v240, v110
	v_add_f32_e64 v127, v240, v111
	v_add_f32_e32 v124, v240, v108
	v_add_f32_e32 v125, v240, v109
	v_add_f32_e32 v122, v240, v106
	v_add_f32_e32 v123, v240, v107
	v_add_f32_e32 v120, v240, v104
	v_add_f32_e32 v121, v240, v105
	v_add_f32_e32 v118, v240, v102
	v_add_f32_e32 v119, v240, v103
	v_add_f32_e32 v116, v240, v100
	v_add_f32_e32 v117, v240, v101
	ds_read_b128 v[240:243], v179 offset:4096
	s_waitcnt lgkmcnt(2)
	v_mfma_f32_32x32x16_bf16 v[98:113], v[232:235], v[130:133], v[98:113]
	v_add_f32_e32 v254, v77, v254
	v_exp_f32_e32 v93, v93
	v_exp_f32_e32 v78, v78
	v_add_u32_e32 v179, v183, v209
	ds_read_b128 v[232:235], v179
	v_mfma_f32_32x32x16_bf16 v[114:129], v[228:231], v[130:133], v[114:129]
	v_add_f32_e32 v255, v93, v255
	v_add_f32_e32 v254, v78, v254
	v_exp_f32_e32 v94, v94
	v_exp_f32_e32 v79, v79
	ds_read_b128 v[228:231], v179 offset:4096
	s_waitcnt lgkmcnt(2)
	v_mfma_f32_32x32x16_bf16 v[98:113], v[236:239], v[134:137], v[98:113]
	v_add_f32_e32 v255, v94, v255
	v_add_f32_e32 v254, v79, v254
	v_exp_f32_e32 v95, v95
	v_exp_f32_e32 v80, v80
	v_add_u32_e32 v179, v183, v226
	ds_read_b128 v[236:239], v179
	v_mfma_f32_32x32x16_bf16 v[114:129], v[240:243], v[134:137], v[114:129]
	v_add_f32_e32 v255, v95, v255
	v_add_f32_e32 v254, v80, v254
	v_exp_f32_e32 v96, v96
	v_exp_f32_e32 v81, v81
	ds_read_b128 v[240:243], v179 offset:4096
	s_waitcnt lgkmcnt(2)
	v_mfma_f32_32x32x16_bf16 v[98:113], v[232:235], v[138:141], v[98:113]
	v_add_f32_e32 v255, v96, v255
	v_add_f32_e32 v254, v81, v254
	v_exp_f32_e32 v97, v97
	v_mfma_f32_32x32x16_bf16 v[114:129], v[228:231], v[138:141], v[114:129]
	v_add_f32_e32 v255, v97, v255
	v_add_f32_e32 v254, v255, v254
	s_waitcnt lgkmcnt(0)
	v_mfma_f32_32x32x16_bf16 v[98:113], v[236:239], v[142:145], v[98:113]
	v_mfma_f32_32x32x16_bf16 v[114:129], v[240:243], v[142:145], v[114:129]
	s_cmp_lg_u32 s4, 0
	s_cbranch_scc0 .LBB0_471
	s_waitcnt vmcnt(4) lgkmcnt(0)
	s_barrier
	s_andn2_b32 s4, s99, s2
	s_cbranch_scc0 .LBB0_460
	v_add_f32_e32 v179, v198, v254
	s_branch .LBB0_464

.LBB0_466:
	s_cmp_lt_i32 s78, s39
	s_cselect_b64 vcc, -1, 0
	s_cselect_b32 s60, s78, s61
	v_cndmask_b32_e64 v228, -v201, v201, vcc
	s_add_i32 s60, s60, s33
	s_lshl_b32 s78, s60, 6
	s_lshl_b32 s80, s78, 1
	s_addk_i32 s62, 0xc000
	s_cmp_lg_u32 s5, 0
	s_cselect_b32 s60, s62, 0x8000
	s_add_i32 s60, s14, s60
	v_lshl_add_u64 v[66:67], v[204:205], 0, s[80:81]
	s_add_i32 m0, s60, 0xc000
	v_lshl_add_u64 v[68:69], v[206:207], 0, s[80:81]
	global_load_lds_dwordx4 v[66:67], off
	s_add_i32 m0, s60, 0xc400
	v_cvt_f32_i32_e32 v66, s78
	global_load_lds_dwordx4 v[68:69], off
	v_exp_f32_e32 v231, v98
	v_add_f32_e32 v66, v155, v66
	v_fma_f32 v230, v228, v66, -v199
	v_add_u32_e32 v229, s10, v218
	v_exp_f32_e32 v233, v114
	v_fma_f32 v66, 0, v228, v230
	v_exp_f32_e32 v234, v99
	v_exp_f32_e32 v235, v115
	v_add_f32_e32 v67, v228, v230
	v_exp_f32_e32 v236, v100
	v_exp_f32_e32 v237, v116
	v_exp_f32_e32 v238, v101
	v_exp_f32_e32 v239, v117
	v_fma_f32 v68, v228, s64, v230
	v_fma_f32 v69, v228, s65, v230
	v_fma_f32 v70, v228, s66, v230
	v_fma_f32 v71, v228, s67, v230
	v_cvt_pk_bf16_f32 v98, v249, v250
	v_cvt_pk_bf16_f32 v99, v195, v251
	v_cvt_pk_bf16_f32 v100, v252, v253
	v_cvt_pk_bf16_f32 v101, v72, v73
	v_cvt_pk_bf16_f32 v114, v90, v91
	v_cvt_pk_bf16_f32 v115, v92, v93
	v_cvt_pk_bf16_f32 v116, v94, v95
	v_cvt_pk_bf16_f32 v117, v96, v97
	v_mul_f32_e32 v232, 0x42000000, v228
	v_exp_f32_e32 v240, v102
	v_exp_f32_e32 v241, v118
	v_exp_f32_e32 v242, v103
	v_exp_f32_e32 v243, v119
	ds_read_b128 v[90:93], v227 offset:53248
	s_waitcnt lgkmcnt(2)
	v_mfma_f32_32x32x16_bf16 v[18:33], v[86:89], v[74:77], v[18:33]
	v_add_f32_e32 v254, 0, v231
	v_add_f32_e32 v255, 0, v233
	v_fma_f32 v72, v228, s68, v230
	v_fma_f32 v73, v228, s69, v230
	v_exp_f32_e32 v181, v104
	v_exp_f32_e32 v183, v120
	ds_read_b128 v[86:89], v227 offset:57344
	v_mfma_f32_32x32x16_bf16 v[2:17], v[82:85], v[74:77], v[2:17]
	v_add_f32_e32 v254, v234, v254
	v_add_f32_e32 v255, v235, v255
	v_exp_f32_e32 v195, v105
	v_exp_f32_e32 v200, v121
	ds_read_b128 v[82:85], v227 offset:61440
	s_waitcnt lgkmcnt(2)
	v_mfma_f32_32x32x16_bf16 v[50:65], v[78:81], v[98:101], v[50:65]
	v_add_f32_e32 v254, v236, v254
	v_add_f32_e32 v255, v237, v255
	v_fma_f32 v74, v228, s70, v230
	v_fma_f32 v75, v228, s71, v230
	v_exp_f32_e32 v224, v106
	v_exp_f32_e32 v122, v122
	v_add_u32_e32 v78, v198, v226
	ds_read_b128 v[94:97], v78 offset:49152
	v_mfma_f32_32x32x16_bf16 v[34:49], v[90:93], v[98:101], v[34:49]
	v_add_f32_e32 v254, v238, v254
	v_add_f32_e32 v255, v239, v255
	v_exp_f32_e32 v225, v107
	v_exp_f32_e32 v123, v123
	ds_read_b128 v[90:93], v78 offset:53248
	s_waitcnt lgkmcnt(2)
	v_mfma_f32_32x32x16_bf16 v[18:33], v[86:89], v[98:101], v[18:33]
	v_add_f32_e32 v254, v240, v254
	v_add_f32_e32 v255, v241, v255
	v_fma_f32 v76, v228, s72, v230
	v_fma_f32 v77, v228, s73, v230
	v_exp_f32_e32 v227, v108
	v_exp_f32_e32 v124, v124
	ds_read_b128 v[86:89], v78 offset:57344
	v_mfma_f32_32x32x16_bf16 v[2:17], v[82:85], v[98:101], v[2:17]
	v_add_f32_e32 v254, v242, v254
	v_add_f32_e32 v255, v243, v255
	v_exp_f32_e32 v244, v109
	v_exp_f32_e32 v125, v125
	ds_read_b128 v[98:101], v78 offset:61440
	s_waitcnt lgkmcnt(2)
	v_mfma_f32_32x32x16_bf16 v[50:65], v[94:97], v[114:117], v[50:65]
	v_add_f32_e32 v254, v181, v254
	v_add_f32_e32 v255, v183, v255
	v_fma_f32 v78, v228, s74, v230
	v_fma_f32 v79, v228, s75, v230
	v_exp_f32_e32 v245, v110
	v_exp_f32_e32 v126, v126
	v_add_u32_e32 v80, v229, v149
	ds_read_b128 v[102:105], v80
	v_mfma_f32_32x32x16_bf16 v[34:49], v[90:93], v[114:117], v[34:49]
	v_add_f32_e32 v254, v195, v254
	v_add_f32_e32 v255, v200, v255
	v_exp_f32_e32 v246, v111
	v_exp_f32_e32 v127, v127
	ds_read_b128 v[106:109], v80 offset:4096
	s_waitcnt lgkmcnt(2)
	v_mfma_f32_32x32x16_bf16 v[18:33], v[86:89], v[114:117], v[18:33]
	v_add_f32_e32 v254, v224, v254
	v_add_f32_e32 v255, v122, v255
	v_fma_f32 v80, v228, s76, v230
	v_fma_f32 v81, v228, s77, v230
	v_exp_f32_e32 v247, v112
	v_exp_f32_e32 v128, v128
	v_add_u32_e32 v110, v229, v208
	ds_read_b128 v[118:121], v110
	v_mfma_f32_32x32x16_bf16 v[2:17], v[98:101], v[114:117], v[2:17]
	v_add_f32_e32 v254, v225, v254
	v_add_f32_e32 v255, v123, v255
	v_add_f32_e64 v82, v232, v66
	v_add_f32_e64 v83, v232, v67
	v_add_f32_e64 v96, v232, v80
	v_add_f32_e64 v97, v232, v81
	v_add_f32_e64 v94, v232, v78
	v_add_f32_e64 v95, v232, v79
	v_add_f32_e32 v92, v232, v76
	v_add_f32_e32 v93, v232, v77
	v_add_f32_e32 v90, v232, v74
	v_add_f32_e32 v91, v232, v75
	v_add_f32_e32 v88, v232, v72
	v_add_f32_e32 v89, v232, v73
	v_add_f32_e32 v86, v232, v70
	v_add_f32_e32 v87, v232, v71
	v_add_f32_e32 v84, v232, v68
	v_add_f32_e32 v85, v232, v69
	v_exp_f32_e32 v228, v113
	v_exp_f32_e32 v129, v129
	ds_read_b128 v[98:101], v110 offset:4096
	s_waitcnt lgkmcnt(2)
	v_mfma_f32_32x32x16_bf16 v[66:81], v[102:105], v[130:133], v[66:81]
	v_add_f32_e32 v254, v227, v254
	v_add_f32_e32 v255, v124, v255
	v_add_f32_e32 v254, v244, v254
	v_add_u32_e32 v110, v229, v209
	ds_read_b128 v[102:105], v110
	v_mfma_f32_32x32x16_bf16 v[82:97], v[106:109], v[130:133], v[82:97]
	v_add_f32_e32 v255, v125, v255
	v_add_f32_e32 v254, v245, v254
	v_add_f32_e32 v255, v126, v255
	ds_read_b128 v[106:109], v110 offset:4096
	s_waitcnt lgkmcnt(2)
	v_mfma_f32_32x32x16_bf16 v[66:81], v[118:121], v[134:137], v[66:81]
	v_add_f32_e32 v254, v246, v254
	v_add_f32_e32 v255, v127, v255
	v_add_f32_e32 v254, v247, v254
	v_add_u32_e32 v114, v229, v226
	ds_read_b128 v[110:113], v114
	v_mfma_f32_32x32x16_bf16 v[82:97], v[98:101], v[134:137], v[82:97]
	v_add_f32_e32 v255, v128, v255
	v_add_f32_e32 v254, v228, v254
	v_add_f32_e32 v255, v129, v255
	v_add_f32_e32 v254, v255, v254
	ds_read_b128 v[98:101], v114 offset:4096
	s_waitcnt lgkmcnt(2)
	v_mfma_f32_32x32x16_bf16 v[66:81], v[102:105], v[138:141], v[66:81]
	v_cvt_pk_bf16_f32 v114, v122, v123
	v_cvt_pk_bf16_f32 v115, v124, v125
	v_cvt_pk_bf16_f32 v116, v126, v127
	v_cvt_pk_bf16_f32 v117, v128, v129
	v_mfma_f32_32x32x16_bf16 v[82:97], v[106:109], v[138:141], v[82:97]
	v_cvt_pk_bf16_f32 v106, v224, v225
	v_cvt_pk_bf16_f32 v107, v227, v244
	v_cvt_pk_bf16_f32 v108, v245, v246
	v_cvt_pk_bf16_f32 v109, v247, v228
	s_waitcnt lgkmcnt(0)
	v_mfma_f32_32x32x16_bf16 v[66:81], v[110:113], v[142:145], v[66:81]
	v_cvt_pk_bf16_f32 v110, v233, v235
	v_cvt_pk_bf16_f32 v111, v237, v239
	v_cvt_pk_bf16_f32 v112, v241, v243
	v_cvt_pk_bf16_f32 v113, v183, v200
	v_mfma_f32_32x32x16_bf16 v[82:97], v[98:101], v[142:145], v[82:97]
	s_add_i32 s10, s4, 1
	s_cmp_lg_u32 s4, 2
	s_cselect_b32 s62, s10, 0
	s_add_i32 s4, s5, 1
	s_cmp_lg_u32 s5, 2
	s_cselect_b32 s10, s4, 0
	s_add_i32 s34, s34, 2
	v_add_f32_e32 v198, v179, v254
	v_cvt_pk_bf16_f32 v98, v231, v234
	v_cvt_pk_bf16_f32 v99, v236, v238
	v_cvt_pk_bf16_f32 v100, v240, v242
	v_cvt_pk_bf16_f32 v101, v181, v195
	s_cmp_ge_i32 s61, s48
	s_cbranch_scc1 .LBB0_473
	s_mov_b32 s60, s63
	s_add_i32 s61, s34, -2
	s_cmp_gt_i32 s61, s48
	s_cbranch_scc1 .LBB0_469
.LBB0_468:
	s_waitcnt vmcnt(4) lgkmcnt(0)
	s_barrier
	s_cmp_lg_u32 s99, 0
	s_cbranch_scc1 .Lattn_A_fast
	s_branch .LBB0_452

.LBB0_471:
	s_mov_b64 s[4:5], -1
	s_waitcnt vmcnt(2) lgkmcnt(0)
	s_barrier
	s_andn2_b64 vcc, exec, s[2:3]
	s_cbranch_vccz .LBB0_461
	s_branch .LBB0_462
